# sel far tiles: QK MFMAs start from C = (on ? cbias-m : -1e30): no per-element sub/alpha on the common path
# speedup vs baseline: 1.0090x; 1.0090x over previous
; template <int NDT, int MODE, bool ALLON>
; DI void attn_tile(const bf16_t* Kl, int kst, const bf16_t* Vl, const bf16x8 (&q)[4], f32x16 (&O)[NDT], float& m, float& l,
;                   int kbase, int qp, int win, float cbias, const float* tab, bool lane_on) {
;     ...
;   for (int ks = 0; ks < 4; ++ks) {
;     const bf16x8 k0 = *(const bf16x8*)(Kl + lr * kst + ks * 16 + lh * 8);
;     const bf16x8 k1 = *(const bf16x8*)(Kl + (32 + lr) * kst + ks * 16 + lh * 8);
;     s[0] = MFMA32(k0, q[ks], s[0]);
;     s[1] = MFMA32(k1, q[ks], s[1]);
;   }
;   float alpha, psum = 0.f;
;   if (MODE == 0) {
;     float tmax = fmaxf(s[0][0], s[1][0]);
; #pragma unroll
;     for (int i = 1; i < 16; ++i) tmax = fmaxf(tmax, fmaxf(s[0][i], s[1][i]));
;     tmax = fmaxf(tmax, xor32(tmax)) + cbias;
;     if (!ALLON) tmax = lane_on ? tmax : -1e30f;
;     const float mn = fmaxf(m, tmax);
;     alpha = ex2(m - mn);
;     m = mn;
;     const float mc = (ALLON || lane_on) ? mn - cbias : 1e30f;
; #pragma unroll
;     for (int st = 0; st < 2; ++st)
; #pragma unroll
;       for (int i = 0; i < 16; ++i) { const float pe = ex2(s[st][i] - mc); psum += pe; s[st][i] = pe; }
;   } else {
;     float tmax = -1e30f;
; #pragma unroll
;     for (int st = 0; st < 2; ++st)
; #pragma unroll
;       for (int i = 0; i < 16; ++i) {
;         const int key = kbase + st * 32 + 8 * (i >> 2) + 4 * lh + (i & 3);
;         float v;
;         if (MODE == 1) {
;           const int dist = qp - key;
;           const bool ok = (ALLON || lane_on) && dist >= 0 && dist < win;
;           const int di = dist < 0 ? 0 : (dist > 128 ? 128 : dist);
;           v = ok ? s[st][i] + tab[di] : -1e30f;
;         } else {
;           v = (16 * key + 31 <= qp) ? s[st][i] : -1e30f;
;         }
;         s[st][i] = v;
;         tmax = fmaxf(tmax, v);
;       }
;     tmax = fmaxf(tmax, xor32(tmax));
;     const float mn = fmaxf(m, tmax);
;     alpha = ex2(m - mn);
;     m = mn;
; #pragma unroll
;     for (int st = 0; st < 2; ++st)
; #pragma unroll
;       for (int i = 0; i < 16; ++i) {
;         const float pe = s[st][i] > -5e29f ? ex2(s[st][i] - mn) : 0.f;
;         psum += pe;
;         s[st][i] = pe;
;       }
;   }
;   l = l * alpha + psum;
;   if (__ballot(alpha != 1.f)) {
; #pragma unroll
;     for (int dt = 0; dt < NDT; ++dt)
; #pragma unroll
;       for (int i = 0; i < 16; ++i) O[dt][i] *= alpha;
.LBB0_720:
	v_ffbl_b32_e32 v1, v1
	v_ffbl_b32_e32 v0, v0
	v_add_u32_e64 v1, v1, 32 clamp
	v_min_u32_e32 v0, v1, v0
	v_lshlrev_b32_e32 v32, 6, v0
	v_cmp_le_i32_e32 vcc, v32, v138
	s_waitcnt lgkmcnt(0)
	s_barrier
	s_and_saveexec_b64 s[8:9], vcc
	s_cbranch_execz .LBB0_797
	v_lshrrev_b64 v[0:1], v0, v[96:97]
	v_and_b32_e32 v0, 1, v0
	v_cmp_eq_u32_e64 s[4:5], 1, v0
	v_cmp_ne_u32_e32 vcc, 0, v0
	s_cbranch_vccz .LBB0_797
	v_cmp_le_i32_e32 vcc, v32, v137
	s_and_saveexec_b64 s[28:29], vcc
	s_xor_b64 s[28:29], exec, s[28:29]
	s_cbranch_execz .LBB0_727
	v_mov_b32_e32 v0, v195
	ds_read_b32 v144, v135 offset:37376
	s_nop 0
	v_and_b32_e32 v1, 31, v0
	v_lshrrev_b32_e32 v0, 2, v0
	v_mul_u32_u24_e32 v1, 0x48, v1
	v_and_b32_e32 v143, 8, v0
	v_lshlrev_b32_e32 v142, 1, v1
	v_lshlrev_b32_e32 v0, 1, v143
	v_add3_u32 v4, s45, v142, v0
	ds_read_b128 v[196:199], v4
	ds_read_b128 v[200:203], v4 offset:4608
	ds_read_b128 v[204:207], v4 offset:32
	ds_read_b128 v[208:211], v4 offset:4640
	ds_read_b128 v[212:215], v4 offset:64
	ds_read_b128 v[216:219], v4 offset:4672
	ds_read_b128 v[152:155], v4 offset:4704
	ds_read_b128 v[156:159], v4 offset:96
	s_waitcnt lgkmcnt(8)
	v_sub_f32_e32 v145, v144, v88
	v_cmp_neq_f32_e32 vcc, v88, v232
	s_nop 1
	v_cndmask_b32_e32 v145, 0, v145, vcc
	v_cndmask_b32_e64 v145, v232, v145, s[4:5]
	v_mov_b32_e32 v236, v145
	v_mov_b32_e32 v237, v145
	v_mov_b32_e32 v238, v145
	v_mov_b32_e32 v239, v145
	v_mov_b32_e32 v240, v145
	v_mov_b32_e32 v241, v145
	v_mov_b32_e32 v242, v145
	v_mov_b32_e32 v243, v145
	v_mov_b32_e32 v244, v145
	v_mov_b32_e32 v245, v145
	v_mov_b32_e32 v246, v145
	v_mov_b32_e32 v247, v145
	v_mov_b32_e32 v248, v145
	v_mov_b32_e32 v249, v145
	v_mov_b32_e32 v250, v145
	v_mov_b32_e32 v251, v145
	s_nop 1
	s_waitcnt lgkmcnt(7)
	v_mfma_f32_32x32x16_bf16 v[48:63], v[196:199], v[64:67], v[236:251]
	s_waitcnt lgkmcnt(6)
	v_mfma_f32_32x32x16_bf16 v[32:47], v[200:203], v[64:67], v[236:251]
	s_waitcnt lgkmcnt(5)
	v_mfma_f32_32x32x16_bf16 v[48:63], v[204:207], v[68:71], v[48:63]
	s_waitcnt lgkmcnt(4)
	v_mfma_f32_32x32x16_bf16 v[32:47], v[208:211], v[68:71], v[32:47]
	s_waitcnt lgkmcnt(3)
	v_mfma_f32_32x32x16_bf16 v[48:63], v[212:215], v[72:75], v[48:63]
	s_waitcnt lgkmcnt(2)
	v_mfma_f32_32x32x16_bf16 v[32:47], v[216:219], v[72:75], v[32:47]
	s_waitcnt lgkmcnt(1)
	v_mfma_f32_32x32x16_bf16 v[32:47], v[152:155], v[76:79], v[32:47]
	s_waitcnt lgkmcnt(0)
	v_mfma_f32_32x32x16_bf16 v[48:63], v[156:159], v[76:79], v[48:63]
	s_nop 8
	v_max3_f32 v0, v32, v33, v34
	v_max3_f32 v0, v0, v35, v36
	v_max3_f32 v0, v0, v37, v38
	v_max3_f32 v0, v0, v39, v40
	v_max3_f32 v0, v0, v41, v42
	v_max3_f32 v0, v0, v43, v44
	v_max3_f32 v0, v0, v45, v46
	v_max_f32_e32 v0, v0, v47
	v_max3_f32 v1, v48, v49, v50
	v_max3_f32 v1, v1, v51, v52
	v_max3_f32 v1, v1, v53, v54
	v_max3_f32 v1, v1, v55, v56
	v_max3_f32 v1, v1, v57, v58
	v_max3_f32 v1, v1, v59, v60
	v_max3_f32 v1, v1, v61, v62
	v_max_f32_e32 v1, v1, v63
	v_max_f32_e32 v0, v0, v1
	ds_bpermute_b32 v1, v91, v0
	s_waitcnt lgkmcnt(0)
	v_max_f32_e32 v1, v1, v1
	v_max_f32_e32 v0, v0, v1
	v_cmp_lt_f32_e32 vcc, 0x41000000, v0
	v_cmp_eq_f32_e64 s[48:49], v88, v232
	s_nop 1
	s_and_b64 s[48:49], s[48:49], s[4:5]
	s_or_b64 s[50:51], vcc, s[48:49]
	s_cbranch_scc0 .Lsel_fast
	v_sub_f32_e32 v48, v48, v145
	v_sub_f32_e32 v49, v49, v145
	v_sub_f32_e32 v50, v50, v145
	v_sub_f32_e32 v51, v51, v145
	v_sub_f32_e32 v52, v52, v145
	v_sub_f32_e32 v53, v53, v145
	v_sub_f32_e32 v54, v54, v145
	v_sub_f32_e32 v55, v55, v145
	v_sub_f32_e32 v56, v56, v145
	v_sub_f32_e32 v57, v57, v145
	v_sub_f32_e32 v58, v58, v145
	v_sub_f32_e32 v59, v59, v145
	v_sub_f32_e32 v60, v60, v145
	v_sub_f32_e32 v61, v61, v145
	v_sub_f32_e32 v62, v62, v145
	v_sub_f32_e32 v63, v63, v145
	v_sub_f32_e32 v32, v32, v145
	v_sub_f32_e32 v33, v33, v145
	v_sub_f32_e32 v34, v34, v145
	v_sub_f32_e32 v35, v35, v145
	v_sub_f32_e32 v36, v36, v145
	v_sub_f32_e32 v37, v37, v145
	v_sub_f32_e32 v38, v38, v145
	v_sub_f32_e32 v39, v39, v145
	v_sub_f32_e32 v40, v40, v145
	v_sub_f32_e32 v41, v41, v145
	v_sub_f32_e32 v42, v42, v145
	v_sub_f32_e32 v43, v43, v145
	v_sub_f32_e32 v44, v44, v145
	v_sub_f32_e32 v45, v45, v145
	v_sub_f32_e32 v46, v46, v145
	v_sub_f32_e32 v47, v47, v145
	v_sub_f32_e32 v0, v0, v145
	v_add_f32_e32 v0, v144, v0
	v_cndmask_b32_e64 v0, v232, v0, s[4:5]
	v_add_f32_e32 v1, 0x41000000, v88
	v_cmp_gt_f32_e32 vcc, v0, v1
	s_nop 1
	v_cndmask_b32_e32 v141, v88, v0, vcc
	v_sub_f32_e32 v0, v88, v141
	v_exp_f32_e32 v88, v0
	s_nop 0
	v_cmp_neq_f32_e32 vcc, 1.0, v88
	s_cbranch_vccz .LBB0_799
	v_pk_mul_f32 v[160:161], v[160:161], v[88:89] op_sel_hi:[1,0]
	v_pk_mul_f32 v[162:163], v[162:163], v[88:89] op_sel_hi:[1,0]
	v_pk_mul_f32 v[164:165], v[164:165], v[88:89] op_sel_hi:[1,0]
	v_pk_mul_f32 v[166:167], v[166:167], v[88:89] op_sel_hi:[1,0]
	v_pk_mul_f32 v[168:169], v[168:169], v[88:89] op_sel_hi:[1,0]
	v_pk_mul_f32 v[170:171], v[170:171], v[88:89] op_sel_hi:[1,0]
	v_pk_mul_f32 v[172:173], v[172:173], v[88:89] op_sel_hi:[1,0]
	v_pk_mul_f32 v[174:175], v[174:175], v[88:89] op_sel_hi:[1,0]
	v_pk_mul_f32 v[176:177], v[176:177], v[88:89] op_sel_hi:[1,0]
	v_pk_mul_f32 v[178:179], v[178:179], v[88:89] op_sel_hi:[1,0]
	v_pk_mul_f32 v[180:181], v[180:181], v[88:89] op_sel_hi:[1,0]
	v_pk_mul_f32 v[182:183], v[182:183], v[88:89] op_sel_hi:[1,0]
	v_pk_mul_f32 v[184:185], v[184:185], v[88:89] op_sel_hi:[1,0]
	v_pk_mul_f32 v[186:187], v[186:187], v[88:89] op_sel_hi:[1,0]
	v_pk_mul_f32 v[188:189], v[188:189], v[88:89] op_sel_hi:[1,0]
	v_pk_mul_f32 v[190:191], v[190:191], v[88:89] op_sel_hi:[1,0]
	s_cbranch_execnz .LBB0_726
; template <int NDT, int MODE, bool ALLON>
; DI void attn_tile(const bf16_t* Kl, int kst, const bf16_t* Vl, const bf16x8 (&q)[4], f32x16 (&O)[NDT], float& m, float& l,
;                   int kbase, int qp, int win, float cbias, const float* tab, bool lane_on) {
;     ...
;     const float mc = (ALLON || lane_on) ? mn - cbias : 1e30f;
; #pragma unroll
;     for (int st = 0; st < 2; ++st)
; #pragma unroll
;       for (int i = 0; i < 16; ++i) { const float pe = ex2(s[st][i] - mc); psum += pe; s[st][i] = pe; }
;   } else {
;     float tmax = -1e30f;
; #pragma unroll
;     for (int st = 0; st < 2; ++st)
; #pragma unroll
;       for (int i = 0; i < 16; ++i) {
;         const int key = kbase + st * 32 + 8 * (i >> 2) + 4 * lh + (i & 3);
;         float v;
;         if (MODE == 1) {
;           const int dist = qp - key;
;           const bool ok = (ALLON || lane_on) && dist >= 0 && dist < win;
;           const int di = dist < 0 ? 0 : (dist > 128 ? 128 : dist);
;           v = ok ? s[st][i] + tab[di] : -1e30f;
;         } else {
;           v = (16 * key + 31 <= qp) ? s[st][i] : -1e30f;
;         }
;         s[st][i] = v;
;         tmax = fmaxf(tmax, v);
;       }
;     tmax = fmaxf(tmax, xor32(tmax));
;     const float mn = fmaxf(m, tmax);
;     alpha = ex2(m - mn);
;     m = mn;
; #pragma unroll
;     for (int st = 0; st < 2; ++st)
; #pragma unroll
;       for (int i = 0; i < 16; ++i) {
;         const float pe = s[st][i] > -5e29f ? ex2(s[st][i] - mn) : 0.f;
;         psum += pe;
;         s[st][i] = pe;
;       }
;   }
;   l = l * alpha + psum;
;   if (__ballot(alpha != 1.f)) {
; #pragma unroll
;     for (int dt = 0; dt < NDT; ++dt)
; #pragma unroll
;       for (int i = 0; i < 16; ++i) O[dt][i] *= alpha;
;   }
; #pragma unroll
;   for (int st = 0; st < 2; ++st)
; #pragma unroll
;     for (int sk = 0; sk < 2; ++sk) {
;       u32x4 pu;
;       pu[0] = pack2(s[st][8 * sk + 0], s[st][8 * sk + 1]);
;       pu[1] = pack2(s[st][8 * sk + 2], s[st][8 * sk + 3]);
;       pu[2] = pack2(s[st][8 * sk + 4], s[st][8 * sk + 5]);
;       pu[3] = pack2(s[st][8 * sk + 6], s[st][8 * sk + 7]);
;       const bf16x8 pf = __builtin_bit_cast(bf16x8, pu);
; #pragma unroll
;       for (int dt = 0; dt < NDT; ++dt) {
;         const bf16_t* vp = Vl + (dt * 32 + lr) * 72 + st * 32 + sk * 16 + 4 * lh;
;         const uint2 v0 = *(const uint2*)(vp);
;         const uint2 v1 = *(const uint2*)(vp + 8);
.LBB0_725:
.LBB0_726:
	v_sub_f32_e32 v100, v141, v144
	v_mov_b32_e32 v101, 0x7149f2ca
	v_cndmask_b32_e64 v100, v101, v100, s[4:5]
	v_sub_f32_e32 v48, v48, v100
	v_exp_f32_e32 v48, v48
	v_sub_f32_e32 v49, v49, v100
	v_exp_f32_e32 v49, v49
	v_sub_f32_e32 v50, v50, v100
	v_exp_f32_e32 v50, v50
	v_sub_f32_e32 v51, v51, v100
	v_exp_f32_e32 v51, v51
	v_sub_f32_e32 v52, v52, v100
	v_add_f32_e32 v101, 0, v48
	v_exp_f32_e32 v52, v52
	v_sub_f32_e32 v53, v53, v100
	v_add_f32_e32 v101, v49, v101
	v_exp_f32_e32 v53, v53
	v_sub_f32_e32 v54, v54, v100
	v_add_f32_e32 v101, v50, v101
	v_exp_f32_e32 v54, v54
	v_sub_f32_e32 v55, v55, v100
	v_add_f32_e32 v101, v51, v101
	v_exp_f32_e32 v55, v55
	v_sub_f32_e32 v56, v56, v100
	v_add_f32_e32 v101, v52, v101
	v_exp_f32_e32 v56, v56
	v_sub_f32_e32 v57, v57, v100
	v_add_f32_e32 v101, v53, v101
	v_exp_f32_e32 v57, v57
	v_sub_f32_e32 v58, v58, v100
	v_add_f32_e32 v101, v54, v101
	v_exp_f32_e32 v58, v58
	v_sub_f32_e32 v59, v59, v100
	v_add_f32_e32 v101, v55, v101
	v_exp_f32_e32 v59, v59
	v_sub_f32_e32 v60, v60, v100
	v_add_f32_e32 v101, v56, v101
	v_exp_f32_e32 v60, v60
	v_sub_f32_e32 v61, v61, v100
	v_add_f32_e32 v101, v57, v101
	v_exp_f32_e32 v61, v61
	v_sub_f32_e32 v62, v62, v100
	v_add_f32_e32 v101, v58, v101
	v_exp_f32_e32 v62, v62
	v_sub_f32_e32 v63, v63, v100
	v_add_f32_e32 v101, v59, v101
	v_exp_f32_e32 v63, v63
	v_sub_f32_e32 v32, v32, v100
	v_add_f32_e32 v101, v60, v101
	v_exp_f32_e32 v102, v32
	v_add_f32_e32 v101, v61, v101
	v_add_f32_e32 v101, v62, v101
	v_add_f32_e32 v101, v63, v101
	v_sub_f32_e32 v33, v33, v100
	v_add_f32_e32 v32, v102, v101
	v_exp_f32_e32 v101, v33
	v_sub_f32_e32 v33, v34, v100
	v_exp_f32_e32 v103, v33
	v_sub_f32_e32 v33, v35, v100
	v_exp_f32_e32 v104, v33
	v_sub_f32_e32 v33, v36, v100
	v_exp_f32_e32 v105, v33
	v_sub_f32_e32 v33, v37, v100
	v_add_f32_e32 v32, v101, v32
	v_exp_f32_e32 v37, v33
	v_sub_f32_e32 v33, v38, v100
	v_add_f32_e32 v32, v103, v32
	v_exp_f32_e32 v106, v33
	v_sub_f32_e32 v33, v39, v100
	v_add_f32_e32 v32, v104, v32
	v_exp_f32_e32 v107, v33
	v_sub_f32_e32 v33, v40, v100
	v_add_f32_e32 v32, v105, v32
	v_exp_f32_e32 v108, v33
	v_sub_f32_e32 v33, v41, v100
	v_add_f32_e32 v32, v37, v32
	v_exp_f32_e32 v109, v33
	v_sub_f32_e32 v33, v42, v100
	v_add_f32_e32 v32, v106, v32
	v_exp_f32_e32 v110, v33
	v_sub_f32_e32 v33, v43, v100
	v_add_f32_e32 v32, v107, v32
	v_exp_f32_e32 v111, v33
	v_sub_f32_e32 v33, v44, v100
	v_add_f32_e32 v32, v108, v32
	v_exp_f32_e32 v112, v33
	v_sub_f32_e32 v33, v45, v100
	v_add_f32_e32 v32, v109, v32
	v_exp_f32_e32 v113, v33
	v_sub_f32_e32 v33, v46, v100
	v_add_f32_e32 v32, v110, v32
	v_exp_f32_e32 v46, v33
	v_sub_f32_e32 v33, v47, v100
	v_add_f32_e32 v32, v111, v32
	v_exp_f32_e32 v47, v33
	v_add_f32_e32 v32, v112, v32
	v_add_f32_e32 v32, v113, v32
	v_add_f32_e32 v32, v46, v32
	v_add_f32_e32 v36, v47, v32
	v_cvt_pk_bf16_f32 v32, v48, v49
	v_add3_u32 v48, s45, v143, v142
	v_add_u32_e32 v49, 0x2000, v48
	ds_read2_b64 v[38:41], v49 offset0:128 offset1:130
	ds_read2_b64 v[42:45], v49 offset0:132 offset1:134
	v_cvt_pk_bf16_f32 v33, v50, v51
	v_cvt_pk_bf16_f32 v34, v52, v53
	v_cvt_pk_bf16_f32 v35, v54, v55
	v_add_u32_e32 v48, 0x3000, v48
	v_fmac_f32_e32 v36, v140, v88
	s_waitcnt lgkmcnt(1)
	v_mfma_f32_32x32x16_bf16 v[160:175], v[38:41], v[32:35], v[160:175]
	ds_read2_b64 v[38:41], v48 offset0:192 offset1:194
	s_waitcnt lgkmcnt(0)
	v_mfma_f32_32x32x16_bf16 v[176:191], v[38:41], v[32:35], v[176:191]
	ds_read2_b64 v[38:41], v48 offset0:196 offset1:198
	v_cvt_pk_bf16_f32 v32, v56, v57
	v_cvt_pk_bf16_f32 v33, v58, v59
	v_cvt_pk_bf16_f32 v34, v60, v61
	v_cvt_pk_bf16_f32 v35, v62, v63
	s_waitcnt lgkmcnt(0)
	s_nop 0
	v_mfma_f32_32x32x16_bf16 v[176:191], v[38:41], v[32:35], v[176:191]
	ds_read2_b64 v[38:41], v49 offset0:136 offset1:138
	v_mfma_f32_32x32x16_bf16 v[160:175], v[42:45], v[32:35], v[160:175]
	v_cvt_pk_bf16_f32 v32, v102, v101
	v_cvt_pk_bf16_f32 v33, v103, v104
	v_cvt_pk_bf16_f32 v34, v105, v37
	v_cvt_pk_bf16_f32 v35, v106, v107
	s_waitcnt lgkmcnt(0)
	s_nop 0
	v_mfma_f32_32x32x16_bf16 v[160:175], v[38:41], v[32:35], v[160:175]
	ds_read2_b64 v[38:41], v48 offset0:200 offset1:202
	s_waitcnt lgkmcnt(0)
	v_mfma_f32_32x32x16_bf16 v[176:191], v[38:41], v[32:35], v[176:191]
	ds_read2_b64 v[38:41], v49 offset0:140 offset1:142
	v_cvt_pk_bf16_f32 v32, v108, v109
	v_cvt_pk_bf16_f32 v33, v110, v111
	v_cvt_pk_bf16_f32 v34, v112, v113
	v_cvt_pk_bf16_f32 v35, v46, v47
	s_waitcnt lgkmcnt(0)
	s_nop 0
	v_mfma_f32_32x32x16_bf16 v[160:175], v[38:41], v[32:35], v[160:175]
	ds_read2_b64 v[38:41], v48 offset0:204 offset1:206
	s_waitcnt lgkmcnt(0)
	v_mfma_f32_32x32x16_bf16 v[176:191], v[38:41], v[32:35], v[176:191]
	s_branch .LBB0_727
; template <int NDT, int MODE, bool ALLON>
; DI void attn_tile(const bf16_t* Kl, int kst, const bf16_t* Vl, const bf16x8 (&q)[4], f32x16 (&O)[NDT], float& m, float& l,
;                   int kbase, int qp, int win, float cbias, const float* tab, bool lane_on) {
;     ...
;     const float mc = (ALLON || lane_on) ? mn - cbias : 1e30f;
; #pragma unroll
;     for (int st = 0; st < 2; ++st)
; #pragma unroll
;       for (int i = 0; i < 16; ++i) { const float pe = ex2(s[st][i] - mc); psum += pe; s[st][i] = pe; }
;   } else {
;     float tmax = -1e30f;
; #pragma unroll
;     for (int st = 0; st < 2; ++st)
; #pragma unroll
;       for (int i = 0; i < 16; ++i) {
;         const int key = kbase + st * 32 + 8 * (i >> 2) + 4 * lh + (i & 3);
;         float v;
;         if (MODE == 1) {
;           const int dist = qp - key;
;           const bool ok = (ALLON || lane_on) && dist >= 0 && dist < win;
;           const int di = dist < 0 ? 0 : (dist > 128 ? 128 : dist);
;           v = ok ? s[st][i] + tab[di] : -1e30f;
;         } else {
;           v = (16 * key + 31 <= qp) ? s[st][i] : -1e30f;
;         }
;         s[st][i] = v;
;         tmax = fmaxf(tmax, v);
;       }
;     tmax = fmaxf(tmax, xor32(tmax));
;     const float mn = fmaxf(m, tmax);
;     alpha = ex2(m - mn);
;     m = mn;
; #pragma unroll
;     for (int st = 0; st < 2; ++st)
; #pragma unroll
;       for (int i = 0; i < 16; ++i) {
;         const float pe = s[st][i] > -5e29f ? ex2(s[st][i] - mn) : 0.f;
;         psum += pe;
;         s[st][i] = pe;
;       }
;   }
;   l = l * alpha + psum;
;   if (__ballot(alpha != 1.f)) {
; #pragma unroll
;     for (int dt = 0; dt < NDT; ++dt)
; #pragma unroll
;       for (int i = 0; i < 16; ++i) O[dt][i] *= alpha;
;   }
; #pragma unroll
;   for (int st = 0; st < 2; ++st)
; #pragma unroll
;     for (int sk = 0; sk < 2; ++sk) {
;       u32x4 pu;
;       pu[0] = pack2(s[st][8 * sk + 0], s[st][8 * sk + 1]);
;       pu[1] = pack2(s[st][8 * sk + 2], s[st][8 * sk + 3]);
;       pu[2] = pack2(s[st][8 * sk + 4], s[st][8 * sk + 5]);
;       pu[3] = pack2(s[st][8 * sk + 6], s[st][8 * sk + 7]);
;       const bf16x8 pf = __builtin_bit_cast(bf16x8, pu);
; #pragma unroll
;       for (int dt = 0; dt < NDT; ++dt) {
;         const bf16_t* vp = Vl + (dt * 32 + lr) * 72 + st * 32 + sk * 16 + 4 * lh;
;         const uint2 v0 = *(const uint2*)(vp);
;         const uint2 v1 = *(const uint2*)(vp + 8);
.Lsel_fast:
	v_mov_b32_e32 v141, v88
	v_exp_f32_e32 v48, v48
	v_exp_f32_e32 v49, v49
	v_exp_f32_e32 v50, v50
	v_exp_f32_e32 v51, v51
	v_add_f32_e32 v101, 0, v48
	v_exp_f32_e32 v52, v52
	v_add_f32_e32 v101, v49, v101
	v_exp_f32_e32 v53, v53
	v_add_f32_e32 v101, v50, v101
	v_exp_f32_e32 v54, v54
	v_add_f32_e32 v101, v51, v101
	v_exp_f32_e32 v55, v55
	v_add_f32_e32 v101, v52, v101
	v_exp_f32_e32 v56, v56
	v_add_f32_e32 v101, v53, v101
	v_exp_f32_e32 v57, v57
	v_add_f32_e32 v101, v54, v101
	v_exp_f32_e32 v58, v58
	v_add_f32_e32 v101, v55, v101
	v_exp_f32_e32 v59, v59
	v_add_f32_e32 v101, v56, v101
	v_exp_f32_e32 v60, v60
	v_add_f32_e32 v101, v57, v101
	v_exp_f32_e32 v61, v61
	v_add_f32_e32 v101, v58, v101
	v_exp_f32_e32 v62, v62
	v_add_f32_e32 v101, v59, v101
	v_exp_f32_e32 v63, v63
	v_add_f32_e32 v101, v60, v101
	v_exp_f32_e32 v102, v32
	v_add_f32_e32 v101, v61, v101
	v_add_f32_e32 v101, v62, v101
	v_add_f32_e32 v101, v63, v101
	v_add_f32_e32 v32, v102, v101
	v_exp_f32_e32 v101, v33
	v_exp_f32_e32 v103, v34
	v_exp_f32_e32 v104, v35
	v_exp_f32_e32 v105, v36
	v_add_f32_e32 v32, v101, v32
	v_exp_f32_e32 v37, v37
	v_add_f32_e32 v32, v103, v32
	v_exp_f32_e32 v106, v38
	v_add_f32_e32 v32, v104, v32
	v_exp_f32_e32 v107, v39
	v_add_f32_e32 v32, v105, v32
	v_exp_f32_e32 v108, v40
	v_add_f32_e32 v32, v37, v32
	v_exp_f32_e32 v109, v41
	v_add_f32_e32 v32, v106, v32
	v_exp_f32_e32 v110, v42
	v_add_f32_e32 v32, v107, v32
	v_exp_f32_e32 v111, v43
	v_add_f32_e32 v32, v108, v32
	v_exp_f32_e32 v112, v44
	v_add_f32_e32 v32, v109, v32
	v_exp_f32_e32 v113, v45
	v_add_f32_e32 v32, v110, v32
	v_exp_f32_e32 v46, v46
	v_add_f32_e32 v32, v111, v32
	v_exp_f32_e32 v47, v47
	v_add_f32_e32 v32, v112, v32
	v_add_f32_e32 v32, v113, v32
	v_add_f32_e32 v32, v46, v32
	v_add_f32_e32 v36, v47, v32
	v_cvt_pk_bf16_f32 v32, v48, v49
	v_add3_u32 v48, s45, v143, v142
	v_add_u32_e32 v49, 0x2000, v48
	ds_read2_b64 v[38:41], v49 offset0:128 offset1:130
	ds_read2_b64 v[42:45], v49 offset0:132 offset1:134
	v_cvt_pk_bf16_f32 v33, v50, v51
	v_cvt_pk_bf16_f32 v34, v52, v53
	v_cvt_pk_bf16_f32 v35, v54, v55
	v_add_u32_e32 v48, 0x3000, v48
	v_add_f32_e32 v36, v36, v140
	s_waitcnt lgkmcnt(1)
	v_mfma_f32_32x32x16_bf16 v[160:175], v[38:41], v[32:35], v[160:175]
	ds_read2_b64 v[38:41], v48 offset0:192 offset1:194
	s_waitcnt lgkmcnt(0)
	v_mfma_f32_32x32x16_bf16 v[176:191], v[38:41], v[32:35], v[176:191]
	ds_read2_b64 v[38:41], v48 offset0:196 offset1:198
	v_cvt_pk_bf16_f32 v32, v56, v57
	v_cvt_pk_bf16_f32 v33, v58, v59
	v_cvt_pk_bf16_f32 v34, v60, v61
	v_cvt_pk_bf16_f32 v35, v62, v63
	s_waitcnt lgkmcnt(0)
	s_nop 0
	v_mfma_f32_32x32x16_bf16 v[176:191], v[38:41], v[32:35], v[176:191]
	ds_read2_b64 v[38:41], v49 offset0:136 offset1:138
	v_mfma_f32_32x32x16_bf16 v[160:175], v[42:45], v[32:35], v[160:175]
	v_cvt_pk_bf16_f32 v32, v102, v101
	v_cvt_pk_bf16_f32 v33, v103, v104
	v_cvt_pk_bf16_f32 v34, v105, v37
	v_cvt_pk_bf16_f32 v35, v106, v107
	s_waitcnt lgkmcnt(0)
	s_nop 0
	v_mfma_f32_32x32x16_bf16 v[160:175], v[38:41], v[32:35], v[160:175]
	ds_read2_b64 v[38:41], v48 offset0:200 offset1:202
	s_waitcnt lgkmcnt(0)
	v_mfma_f32_32x32x16_bf16 v[176:191], v[38:41], v[32:35], v[176:191]
	ds_read2_b64 v[38:41], v49 offset0:140 offset1:142
	v_cvt_pk_bf16_f32 v32, v108, v109
	v_cvt_pk_bf16_f32 v33, v110, v111
	v_cvt_pk_bf16_f32 v34, v112, v113
	v_cvt_pk_bf16_f32 v35, v46, v47
	s_waitcnt lgkmcnt(0)
	s_nop 0
	v_mfma_f32_32x32x16_bf16 v[160:175], v[38:41], v[32:35], v[160:175]
	ds_read2_b64 v[38:41], v48 offset0:204 offset1:206
	s_waitcnt lgkmcnt(0)
	v_mfma_f32_32x32x16_bf16 v[176:191], v[38:41], v[32:35], v[176:191]
